# in-proj and gate/up K-loops: A-fragment LDS read address adds folded into ds_read offsets on one precomputed base (4 fewer VALU per 128 MFMAs)
# baseline (speedup 1.0000x reference)
; #define PG8_STAGE(bufoff, gbase, voff) do { _Pragma("unroll") for (int _i = 0; _i < 2; ++_i) \
;         __builtin_amdgcn_global_load_lds((const unsigned*)((const char*)(gbase) + (voff)[_i]), (PG8_LAS unsigned*)(lds + (bufoff) + ldsw + _i * 8192), 16, 0, 0); } while (0)
; #define PG8_WAIT_V(n) asm volatile("s_waitcnt vmcnt(" #n ")" ::: "memory")
; #define PG8_BAR __builtin_amdgcn_s_barrier()
; template <class Epi, class Sched, bool ALIGN_EPI = false, bool SP2 = false>
; __device__ __forceinline__ void gemm_phase(PG8_LAS unsigned char* lds, const Gemm g, const Sched& S, const Epi& E) {
;     ...
;     for (int i = 0; i < 2; ++i) { int R, C; stage_rc(tid * 16 + i * 8192, R, C); const int Rb = Epi::PERM ? ((R & ~31) + perm32(R & 31)) : R;
;         voffA[i] = (unsigned)(R * K + C) * 2u; voffB[i] = (unsigned)(Rb * K + C) * 2u; }
;     const size_t kstep = (size_t)(BK * 2);
;     const size_t hstep = (size_t)HALF * K * 2;
;     const size_t tstep = 2 * hstep;
;     const unsigned ldsw = (unsigned)wid * 1024u;
;     const int aoff = lds_byte(wr * 64 + fr, fq * 8), boff = lds_byte(wc * 32 + fr, fq * 8);
;     ...
;         PG8_WAIT_V(2); PG8_BAR;
;         PG8_STAGE(PG8_SB(1, 0), cB + kstep, voffB); PG8_STAGE(PG8_SA(1, 0), cA + kstep, voffA); PG8_STAGE(PG8_SB(1, 1), cB + hstep + kstep, voffB);
;         PG8_WAIT_V(6); PG8_BAR;
.LBB0_304:
	v_lshrrev_b32_e32 v20, 1, v18
	v_and_b32_e32 v20, 24, v20
	s_add_u32 s16, s16, 0x8800000
	v_and_b32_e32 v19, 15, v18
	v_lshlrev_b32_e32 v21, 1, v20
	v_lshlrev_b32_e32 v18, 2, v18
	s_sext_i32_i16 s51, s18
	s_addc_u32 s17, s17, 0
	v_lshl_or_b32 v1, s24, 6, v19
	v_lshl_or_b32 v19, v19, 6, v21
	s_lshl_b32 s18, s24, 13
	v_and_b32_e32 v18, 32, v18
	v_bitop3_b32 v21, v19, s18, v18 bitop3:0xde
	s_lshl_b32 s18, s23, 5
	s_and_b32 s26, s18, 0x60
	s_lshl_b32 s18, s26, 7
	s_add_i32 m0, s12, 0x18000
	v_lshl_add_u64 v[10:11], v[10:11], 0, s[28:29]
	v_bitop3_b32 v146, v19, s18, v18 bitop3:0xde
	v_add_u32_e32 v252, 0x10000, v146
	s_waitcnt vmcnt(2)
	s_barrier
	global_load_lds_dwordx4 v[10:11], off
	v_lshl_add_u64 v[8:9], v[8:9], 0, s[28:29]
	s_add_i32 m0, s12, 0x1a000
	s_add_i32 s18, s12, 0x8000
	s_add_i32 s48, s12, 0xa000
	global_load_lds_dwordx4 v[8:9], off
	v_lshl_add_u64 v[4:5], v[4:5], 0, s[28:29]
	s_mov_b32 m0, s18
	s_add_u32 s24, s20, 0x80080
	global_load_lds_dwordx4 v[4:5], off
	v_lshl_add_u64 v[4:5], v[6:7], 0, s[28:29]
	s_mov_b32 m0, s48
	s_addc_u32 s25, s21, 0
	global_load_lds_dwordx4 v[4:5], off
	s_add_i32 m0, s12, 0x1c000
	s_nop 0
	global_load_lds_dwordx4 v2, s[24:25]
	v_lshl_add_u64 v[4:5], s[24:25], 0, v[132:133]
	s_add_i32 m0, s12, 0x1e000
	s_cmpk_lt_u32 s22, 0x100
	global_load_lds_dwordx4 v[4:5], off
	v_lshlrev_b32_e32 v4, 15, v12
	v_and_b32_e32 v4, 0xffff0000, v4
	v_lshl_add_u32 v4, v13, 12, v4
	v_and_b32_e32 v5, 1, v12
	v_lshl_or_b32 v4, v5, 6, v4
	v_lshl_add_u32 v138, v14, 1, v4
	v_lshlrev_b32_e32 v4, 15, v16
	v_and_b32_e32 v4, 0xffff0000, v4
	s_waitcnt vmcnt(6)
	v_lshl_add_u32 v4, v15, 12, v4
	v_and_b32_e32 v5, 1, v16
	v_lshl_or_b32 v4, v5, 6, v4
	s_cselect_b64 s[22:23], -1, 0
	s_ashr_i32 s49, s4, 31
	v_or_b32_e32 v147, s26, v20
	v_mov_b32_e32 v139, v3
	v_lshl_add_u32 v140, v17, 1, v4
	v_mov_b32_e32 v141, v3
	s_mov_b32 s50, 0
	v_add_u32_e32 v148, 0, v21
	s_barrier
	s_branch .LBB0_307

; #define PG8_STAGE(bufoff, gbase, voff) do { _Pragma("unroll") for (int _i = 0; _i < 2; ++_i) \
;         __builtin_amdgcn_global_load_lds((const unsigned*)((const char*)(gbase) + (voff)[_i]), (PG8_LAS unsigned*)(lds + (bufoff) + ldsw + _i * 8192), 16, 0, 0); } while (0)
; #define PG8_LDA(dst, b, h) do { _Pragma("unroll") for (int m = 0; m < 4; ++m) _Pragma("unroll") for (int k = 0; k < 2; ++k) dst[m][k] = *(const PG8_LAS bf16x8*)(lds + PG8_SA(b, h) + aoff + m * 2048 + k * 1024); } while (0)
; #define PG8_LDB(dst, b, h) do { _Pragma("unroll") for (int n = 0; n < 2; ++n) _Pragma("unroll") for (int k = 0; k < 2; ++k) dst[n][k] = *(const PG8_LAS bf16x8*)(lds + PG8_SB(b, h) + boff + n * 2048 + k * 1024); } while (0)
; #define PG8_MMA(ai, bj, At, Bt) do { __builtin_amdgcn_s_setprio(1); _Pragma("unroll") for (int m = 0; m < 4; ++m) _Pragma("unroll") for (int n = 0; n < 2; ++n) _Pragma("unroll") for (int k = 0; k < 2; ++k) \
;         acc[ai][bj][m][n] = __builtin_amdgcn_mfma_f32_16x16x32_bf16(Bt[n][k], At[m][k], acc[ai][bj][m][n], 0, 0, 0); __builtin_amdgcn_s_setprio(0); } while (0)
; #define PG8_WAIT_V(n) asm volatile("s_waitcnt vmcnt(" #n ")" ::: "memory")
; #define PG8_WAIT_L(n) asm volatile("s_waitcnt lgkmcnt(" #n ")" ::: "memory")
; #define PG8_BAR __builtin_amdgcn_s_barrier()
; #define PG8_SCHED __builtin_amdgcn_sched_barrier(0)
; template <class Epi, class Sched, bool ALIGN_EPI = false, bool SP2 = false>
; __device__ __forceinline__ void gemm_phase(PG8_LAS unsigned char* lds, const Gemm g, const Sched& S, const Epi& E) {
;     ...
;             PG8_LDB(B0, 0, 0); PG8_LDB(B1, 0, 1); PG8_SCHED; PG8_LDA(At, 0, 0); PG8_STAGE(PG8_SA(1, 1), a1 + hstep, voffA);
;             PG8_WAIT_V(8); PG8_WAIT_L(0); PG8_BAR; PG8_MMA(0, 0, At, B0); PG8_MMA(0, 1, At, B1); PG8_BAR; PG8_SCHED;
;             PG8_LDA(At, 0, 1); PG8_STAGE(PG8_SB(0, 0), b2, voffB); PG8_STAGE(PG8_SB(0, 1), b2 + hstep, voffB); PG8_STAGE(PG8_SA(0, 0), a2, voffA);
;             PG8_WAIT_V(8); PG8_WAIT_L(0); PG8_BAR; PG8_MMA(1, 0, At, B0); PG8_MMA(1, 1, At, B1); PG8_BAR; PG8_SCHED;
.LBB0_310:
	s_add_u32 s20, s44, 0xfff80080
	s_addc_u32 s21, s45, -1
	s_add_i32 s30, 0, 0x10000
	s_cmp_eq_u32 s56, 28
	s_cselect_b32 s47, s27, s21
	s_cselect_b32 s46, s52, s20
	s_cselect_b32 s21, s25, s55
	s_cselect_b32 s20, s53, s54
	s_add_i32 s57, 0, 0x14000
	ds_read_b128 v[142:145], v252
	ds_read_b128 v[150:153], v252 offset:1024
	ds_read_b128 v[154:157], v252 offset:2048
	ds_read_b128 v[158:161], v252 offset:3072
	ds_read_b128 v[162:165], v252 offset:16384
	ds_read_b128 v[166:169], v252 offset:17408
	ds_read_b128 v[170:173], v252 offset:18432
	ds_read_b128 v[174:177], v252 offset:19456
	s_add_i32 m0, s12, 0xc000
	ds_read_b128 v[178:181], v148
	ds_read_b128 v[182:185], v148 offset:1024
	ds_read_b128 v[186:189], v148 offset:2048
	ds_read_b128 v[190:193], v148 offset:3072
	ds_read_b128 v[194:197], v148 offset:4096
	ds_read_b128 v[198:201], v148 offset:5120
	ds_read_b128 v[202:205], v148 offset:6144
	ds_read_b128 v[206:209], v148 offset:7168
	global_load_lds_dwordx4 v140, s[44:45]
	s_add_i32 m0, s12, 0xe000
	s_nop 0
	global_load_lds_dwordx4 v138, s[44:45]
	s_waitcnt vmcnt(8)
	s_waitcnt lgkmcnt(0)
	s_barrier
	s_setprio 1
	s_waitcnt lgkmcnt(0)
	v_mfma_f32_16x16x32_bf16 v[128:131], v[142:145], v[178:181], v[128:131]
	v_mfma_f32_16x16x32_bf16 v[124:127], v[154:157], v[178:181], v[124:127]
	v_mfma_f32_16x16x32_bf16 v[120:123], v[142:145], v[186:189], v[120:123]
	v_mfma_f32_16x16x32_bf16 v[112:115], v[154:157], v[186:189], v[112:115]
	v_mfma_f32_16x16x32_bf16 v[104:107], v[142:145], v[194:197], v[104:107]
	v_mfma_f32_16x16x32_bf16 v[96:99], v[154:157], v[194:197], v[96:99]
	v_mfma_f32_16x16x32_bf16 v[88:91], v[142:145], v[202:205], v[88:91]
	v_mfma_f32_16x16x32_bf16 v[80:83], v[154:157], v[202:205], v[80:83]
	v_mfma_f32_16x16x32_bf16 v[128:131], v[150:153], v[182:185], v[128:131]
	v_mfma_f32_16x16x32_bf16 v[124:127], v[158:161], v[182:185], v[124:127]
	v_mfma_f32_16x16x32_bf16 v[120:123], v[150:153], v[190:193], v[120:123]
	v_mfma_f32_16x16x32_bf16 v[112:115], v[158:161], v[190:193], v[112:115]
	v_mfma_f32_16x16x32_bf16 v[104:107], v[150:153], v[198:201], v[104:107]
	v_mfma_f32_16x16x32_bf16 v[96:99], v[158:161], v[198:201], v[96:99]
	v_mfma_f32_16x16x32_bf16 v[88:91], v[150:153], v[206:209], v[88:91]
	v_mfma_f32_16x16x32_bf16 v[80:83], v[158:161], v[206:209], v[80:83]
	s_setprio 0
	s_setprio 1
	v_mfma_f32_16x16x32_bf16 v[116:119], v[162:165], v[178:181], v[116:119]
	v_mfma_f32_16x16x32_bf16 v[108:111], v[170:173], v[178:181], v[108:111]
	v_mfma_f32_16x16x32_bf16 v[100:103], v[162:165], v[186:189], v[100:103]
	v_mfma_f32_16x16x32_bf16 v[92:95], v[170:173], v[186:189], v[92:95]
	v_mfma_f32_16x16x32_bf16 v[84:87], v[162:165], v[194:197], v[84:87]
	v_mfma_f32_16x16x32_bf16 v[76:79], v[170:173], v[194:197], v[76:79]
	v_mfma_f32_16x16x32_bf16 v[72:75], v[162:165], v[202:205], v[72:75]
	v_mfma_f32_16x16x32_bf16 v[68:71], v[170:173], v[202:205], v[68:71]
	v_mfma_f32_16x16x32_bf16 v[116:119], v[166:169], v[182:185], v[116:119]
	v_mfma_f32_16x16x32_bf16 v[108:111], v[174:177], v[182:185], v[108:111]
	v_mfma_f32_16x16x32_bf16 v[100:103], v[166:169], v[190:193], v[100:103]
	v_mfma_f32_16x16x32_bf16 v[92:95], v[174:177], v[190:193], v[92:95]
	v_mfma_f32_16x16x32_bf16 v[84:87], v[166:169], v[198:201], v[84:87]
	v_mfma_f32_16x16x32_bf16 v[76:79], v[174:177], v[198:201], v[76:79]
	v_mfma_f32_16x16x32_bf16 v[72:75], v[166:169], v[206:209], v[72:75]
	v_mfma_f32_16x16x32_bf16 v[68:71], v[174:177], v[206:209], v[68:71]
	s_setprio 0
	s_barrier
	s_add_i32 s30, s30, s10
	v_lshl_add_u64 v[210:211], s[20:21], 0, v[2:3]
	s_mov_b32 m0, s30
	ds_read_b128 v[178:181], v148 offset:16384
	ds_read_b128 v[182:185], v148 offset:17408
	ds_read_b128 v[186:189], v148 offset:18432
	ds_read_b128 v[190:193], v148 offset:19456
	ds_read_b128 v[194:197], v148 offset:20480
	ds_read_b128 v[198:201], v148 offset:21504
	ds_read_b128 v[202:205], v148 offset:22528
	ds_read_b128 v[206:209], v148 offset:23552
	global_load_lds_dwordx4 v[210:211], off
	s_add_i32 m0, s30, 0x2000
	s_add_u32 s30, s20, 0x80000
	v_lshl_add_u64 v[212:213], s[20:21], 0, v[132:133]
	s_addc_u32 s31, s21, 0
	s_add_i32 s57, s57, s10
	global_load_lds_dwordx4 v[212:213], off
	s_mov_b32 m0, s57
	v_lshl_add_u64 v[216:217], s[46:47], 0, v[134:135]
	global_load_lds_dwordx4 v2, s[30:31]
	s_add_i32 m0, s57, 0x2000
	s_nop 0
	global_load_lds_dwordx4 v132, s[30:31]
	v_lshl_add_u64 v[214:215], s[46:47], 0, v[136:137]
	s_mov_b32 m0, s12
	s_nop 0
	global_load_lds_dwordx4 v[214:215], off
	s_mov_b32 m0, s13
	s_nop 0
	global_load_lds_dwordx4 v[216:217], off
	s_waitcnt vmcnt(8)
	s_waitcnt lgkmcnt(0)
	s_barrier
; #define PG8_STAGE(bufoff, gbase, voff) do { _Pragma("unroll") for (int _i = 0; _i < 2; ++_i) \
;         __builtin_amdgcn_global_load_lds((const unsigned*)((const char*)(gbase) + (voff)[_i]), (PG8_LAS unsigned*)(lds + (bufoff) + ldsw + _i * 8192), 16, 0, 0); } while (0)
; #define PG8_LDA(dst, b, h) do { _Pragma("unroll") for (int m = 0; m < 4; ++m) _Pragma("unroll") for (int k = 0; k < 2; ++k) dst[m][k] = *(const PG8_LAS bf16x8*)(lds + PG8_SA(b, h) + aoff + m * 2048 + k * 1024); } while (0)
; #define PG8_LDB(dst, b, h) do { _Pragma("unroll") for (int n = 0; n < 2; ++n) _Pragma("unroll") for (int k = 0; k < 2; ++k) dst[n][k] = *(const PG8_LAS bf16x8*)(lds + PG8_SB(b, h) + boff + n * 2048 + k * 1024); } while (0)
; #define PG8_MMA(ai, bj, At, Bt) do { __builtin_amdgcn_s_setprio(1); _Pragma("unroll") for (int m = 0; m < 4; ++m) _Pragma("unroll") for (int n = 0; n < 2; ++n) _Pragma("unroll") for (int k = 0; k < 2; ++k) \
;         acc[ai][bj][m][n] = __builtin_amdgcn_mfma_f32_16x16x32_bf16(Bt[n][k], At[m][k], acc[ai][bj][m][n], 0, 0, 0); __builtin_amdgcn_s_setprio(0); } while (0)
; #define PG8_WAIT_V(n) asm volatile("s_waitcnt vmcnt(" #n ")" ::: "memory")
; #define PG8_WAIT_L(n) asm volatile("s_waitcnt lgkmcnt(" #n ")" ::: "memory")
; #define PG8_BAR __builtin_amdgcn_s_barrier()
; #define PG8_SCHED __builtin_amdgcn_sched_barrier(0)
; template <class Epi, class Sched, bool ALIGN_EPI = false, bool SP2 = false>
; __device__ __forceinline__ void gemm_phase(PG8_LAS unsigned char* lds, const Gemm g, const Sched& S, const Epi& E) {
;     ...
;             PG8_WAIT_V(8); PG8_WAIT_L(0); PG8_BAR; PG8_MMA(1, 0, At, B0); PG8_MMA(1, 1, At, B1); PG8_BAR; PG8_SCHED;
;             PG8_LDB(B0, 1, 0); PG8_LDB(B1, 1, 1); PG8_SCHED; PG8_LDA(At, 1, 0); PG8_STAGE(PG8_SA(0, 1), a2 + hstep, voffA);
;             PG8_WAIT_V(8); PG8_WAIT_L(0); PG8_BAR; PG8_MMA(0, 0, At, B0); PG8_MMA(0, 1, At, B1); PG8_BAR; PG8_SCHED;
	s_setprio 1
	s_waitcnt lgkmcnt(0)
	v_mfma_f32_16x16x32_bf16 v[64:67], v[142:145], v[178:181], v[64:67]
	v_mfma_f32_16x16x32_bf16 v[60:63], v[154:157], v[178:181], v[60:63]
	v_mfma_f32_16x16x32_bf16 v[56:59], v[142:145], v[186:189], v[56:59]
	v_mfma_f32_16x16x32_bf16 v[48:51], v[154:157], v[186:189], v[48:51]
	v_mfma_f32_16x16x32_bf16 v[40:43], v[142:145], v[194:197], v[40:43]
	v_mfma_f32_16x16x32_bf16 v[32:35], v[154:157], v[194:197], v[32:35]
	v_mfma_f32_16x16x32_bf16 v[24:27], v[142:145], v[202:205], v[24:27]
	v_mfma_f32_16x16x32_bf16 v[16:19], v[154:157], v[202:205], v[16:19]
	v_mfma_f32_16x16x32_bf16 v[64:67], v[150:153], v[182:185], v[64:67]
	v_mfma_f32_16x16x32_bf16 v[60:63], v[158:161], v[182:185], v[60:63]
	v_mfma_f32_16x16x32_bf16 v[56:59], v[150:153], v[190:193], v[56:59]
	v_mfma_f32_16x16x32_bf16 v[48:51], v[158:161], v[190:193], v[48:51]
	v_mfma_f32_16x16x32_bf16 v[40:43], v[150:153], v[198:201], v[40:43]
	v_mfma_f32_16x16x32_bf16 v[32:35], v[158:161], v[198:201], v[32:35]
	v_mfma_f32_16x16x32_bf16 v[24:27], v[150:153], v[206:209], v[24:27]
	v_mfma_f32_16x16x32_bf16 v[16:19], v[158:161], v[206:209], v[16:19]
	s_setprio 0
	s_setprio 1
	v_mfma_f32_16x16x32_bf16 v[52:55], v[162:165], v[178:181], v[52:55]
	v_mfma_f32_16x16x32_bf16 v[44:47], v[170:173], v[178:181], v[44:47]
	v_mfma_f32_16x16x32_bf16 v[36:39], v[162:165], v[186:189], v[36:39]
	v_mfma_f32_16x16x32_bf16 v[28:31], v[170:173], v[186:189], v[28:31]
	v_mfma_f32_16x16x32_bf16 v[20:23], v[162:165], v[194:197], v[20:23]
	v_mfma_f32_16x16x32_bf16 v[12:15], v[170:173], v[194:197], v[12:15]
	v_mfma_f32_16x16x32_bf16 v[8:11], v[162:165], v[202:205], v[8:11]
	v_mfma_f32_16x16x32_bf16 v[4:7], v[170:173], v[202:205], v[4:7]
	v_mfma_f32_16x16x32_bf16 v[52:55], v[166:169], v[182:185], v[52:55]
	v_mfma_f32_16x16x32_bf16 v[44:47], v[174:177], v[182:185], v[44:47]
	v_mfma_f32_16x16x32_bf16 v[36:39], v[166:169], v[190:193], v[36:39]
	v_mfma_f32_16x16x32_bf16 v[28:31], v[174:177], v[190:193], v[28:31]
	v_mfma_f32_16x16x32_bf16 v[20:23], v[166:169], v[198:201], v[20:23]
	v_mfma_f32_16x16x32_bf16 v[12:15], v[174:177], v[198:201], v[12:15]
	v_mfma_f32_16x16x32_bf16 v[8:11], v[166:169], v[206:209], v[8:11]
	v_mfma_f32_16x16x32_bf16 v[4:7], v[174:177], v[206:209], v[4:7]
	s_setprio 0
	s_barrier
	s_add_i32 s57, 0, 0x18000
	s_add_i32 s58, 0, 0x1c000
	ds_read_b128 v[142:145], v252 offset:32768
	ds_read_b128 v[150:153], v252 offset:33792
	ds_read_b128 v[154:157], v252 offset:34816
	ds_read_b128 v[158:161], v252 offset:35840
	ds_read_b128 v[162:165], v252 offset:49152
	ds_read_b128 v[166:169], v252 offset:50176
	ds_read_b128 v[170:173], v252 offset:51200
	ds_read_b128 v[174:177], v252 offset:52224
	s_add_u32 s30, s46, 0x80000
	s_addc_u32 s31, s47, 0
	s_mov_b32 m0, s33
	ds_read_b128 v[178:181], v148 offset:32768
	ds_read_b128 v[182:185], v148 offset:33792
	ds_read_b128 v[186:189], v148 offset:34816
	ds_read_b128 v[190:193], v148 offset:35840
	ds_read_b128 v[194:197], v148 offset:36864
	ds_read_b128 v[198:201], v148 offset:37888
	ds_read_b128 v[202:205], v148 offset:38912
	ds_read_b128 v[206:209], v148 offset:39936
	global_load_lds_dwordx4 v136, s[30:31]
	s_mov_b32 m0, s37
	s_nop 0
	global_load_lds_dwordx4 v134, s[30:31]
	s_waitcnt vmcnt(8)
	s_waitcnt lgkmcnt(0)
	s_barrier
	s_setprio 1
	s_waitcnt lgkmcnt(0)
	v_mfma_f32_16x16x32_bf16 v[128:131], v[142:145], v[178:181], v[128:131]
	v_mfma_f32_16x16x32_bf16 v[124:127], v[154:157], v[178:181], v[124:127]
	v_mfma_f32_16x16x32_bf16 v[120:123], v[142:145], v[186:189], v[120:123]
	v_mfma_f32_16x16x32_bf16 v[112:115], v[154:157], v[186:189], v[112:115]
	v_mfma_f32_16x16x32_bf16 v[104:107], v[142:145], v[194:197], v[104:107]
	v_mfma_f32_16x16x32_bf16 v[96:99], v[154:157], v[194:197], v[96:99]
	v_mfma_f32_16x16x32_bf16 v[88:91], v[142:145], v[202:205], v[88:91]
	v_mfma_f32_16x16x32_bf16 v[80:83], v[154:157], v[202:205], v[80:83]
	v_mfma_f32_16x16x32_bf16 v[128:131], v[150:153], v[182:185], v[128:131]
	v_mfma_f32_16x16x32_bf16 v[124:127], v[158:161], v[182:185], v[124:127]
	v_mfma_f32_16x16x32_bf16 v[120:123], v[150:153], v[190:193], v[120:123]
	v_mfma_f32_16x16x32_bf16 v[112:115], v[158:161], v[190:193], v[112:115]
	v_mfma_f32_16x16x32_bf16 v[104:107], v[150:153], v[198:201], v[104:107]
	v_mfma_f32_16x16x32_bf16 v[96:99], v[158:161], v[198:201], v[96:99]
	v_mfma_f32_16x16x32_bf16 v[88:91], v[150:153], v[206:209], v[88:91]
	v_mfma_f32_16x16x32_bf16 v[80:83], v[158:161], v[206:209], v[80:83]
	s_setprio 0
	s_setprio 1
	v_mfma_f32_16x16x32_bf16 v[116:119], v[162:165], v[178:181], v[116:119]
	v_mfma_f32_16x16x32_bf16 v[108:111], v[170:173], v[178:181], v[108:111]
	v_mfma_f32_16x16x32_bf16 v[100:103], v[162:165], v[186:189], v[100:103]
	v_mfma_f32_16x16x32_bf16 v[92:95], v[170:173], v[186:189], v[92:95]
	v_mfma_f32_16x16x32_bf16 v[84:87], v[162:165], v[194:197], v[84:87]
	v_mfma_f32_16x16x32_bf16 v[76:79], v[170:173], v[194:197], v[76:79]
	v_mfma_f32_16x16x32_bf16 v[72:75], v[162:165], v[202:205], v[72:75]
	v_mfma_f32_16x16x32_bf16 v[68:71], v[170:173], v[202:205], v[68:71]
	v_mfma_f32_16x16x32_bf16 v[116:119], v[166:169], v[182:185], v[116:119]
	v_mfma_f32_16x16x32_bf16 v[108:111], v[174:177], v[182:185], v[108:111]
	v_mfma_f32_16x16x32_bf16 v[100:103], v[166:169], v[190:193], v[100:103]
	v_mfma_f32_16x16x32_bf16 v[92:95], v[174:177], v[190:193], v[92:95]
	v_mfma_f32_16x16x32_bf16 v[84:87], v[166:169], v[198:201], v[84:87]
	v_mfma_f32_16x16x32_bf16 v[76:79], v[174:177], v[198:201], v[76:79]
	v_mfma_f32_16x16x32_bf16 v[72:75], v[166:169], v[206:209], v[72:75]
	v_mfma_f32_16x16x32_bf16 v[68:71], v[174:177], v[206:209], v[68:71]
	s_setprio 0
	s_barrier
; #define PG8_STAGE(bufoff, gbase, voff) do { _Pragma("unroll") for (int _i = 0; _i < 2; ++_i) \
;         __builtin_amdgcn_global_load_lds((const unsigned*)((const char*)(gbase) + (voff)[_i]), (PG8_LAS unsigned*)(lds + (bufoff) + ldsw + _i * 8192), 16, 0, 0); } while (0)
; #define PG8_LDA(dst, b, h) do { _Pragma("unroll") for (int m = 0; m < 4; ++m) _Pragma("unroll") for (int k = 0; k < 2; ++k) dst[m][k] = *(const PG8_LAS bf16x8*)(lds + PG8_SA(b, h) + aoff + m * 2048 + k * 1024); } while (0)
; #define PG8_MMA(ai, bj, At, Bt) do { __builtin_amdgcn_s_setprio(1); _Pragma("unroll") for (int m = 0; m < 4; ++m) _Pragma("unroll") for (int n = 0; n < 2; ++n) _Pragma("unroll") for (int k = 0; k < 2; ++k) \
;         acc[ai][bj][m][n] = __builtin_amdgcn_mfma_f32_16x16x32_bf16(Bt[n][k], At[m][k], acc[ai][bj][m][n], 0, 0, 0); __builtin_amdgcn_s_setprio(0); } while (0)
; #define PG8_WAIT_V(n) asm volatile("s_waitcnt vmcnt(" #n ")" ::: "memory")
; #define PG8_WAIT_L(n) asm volatile("s_waitcnt lgkmcnt(" #n ")" ::: "memory")
; #define PG8_BAR __builtin_amdgcn_s_barrier()
; #define PG8_SCHED __builtin_amdgcn_sched_barrier(0)
; template <class Epi, class Sched, bool ALIGN_EPI = false, bool SP2 = false>
; __device__ __forceinline__ void gemm_phase(PG8_LAS unsigned char* lds, const Gemm g, const Sched& S, const Epi& E) {
;     ...
;             PG8_LDA(At, 1, 1); PG8_STAGE(PG8_SB(1, 0), b3, voffB); PG8_STAGE(PG8_SB(1, 1), b3 + hstep, voffB); PG8_STAGE(PG8_SA(1, 0), a3, voffA);
;             PG8_WAIT_V(8); PG8_WAIT_L(0); PG8_BAR; PG8_MMA(1, 0, At, B0); PG8_MMA(1, 1, At, B1); PG8_BAR; PG8_SCHED;
;     ...
;         if constexpr (ALIGN_EPI) { if (wr == 0) PG8_BAR; }
	s_add_i32 s30, s57, s10
	v_lshl_add_u64 v[210:211], v[210:211], 0, s[28:29]
	s_mov_b32 m0, s30
	ds_read_b128 v[178:181], v148 offset:49152
	ds_read_b128 v[182:185], v148 offset:50176
	ds_read_b128 v[186:189], v148 offset:51200
	ds_read_b128 v[190:193], v148 offset:52224
	ds_read_b128 v[194:197], v148 offset:53248
	ds_read_b128 v[198:201], v148 offset:54272
	ds_read_b128 v[202:205], v148 offset:55296
	ds_read_b128 v[206:209], v148 offset:56320
	global_load_lds_dwordx4 v[210:211], off
	s_add_i32 m0, s30, 0x2000
	s_add_u32 s20, s20, 0x80080
	v_lshl_add_u64 v[210:211], v[212:213], 0, s[28:29]
	s_addc_u32 s21, s21, 0
	s_add_i32 s30, s58, s10
	global_load_lds_dwordx4 v[210:211], off
	s_mov_b32 m0, s30
	s_nop 0
	global_load_lds_dwordx4 v2, s[20:21]
	s_add_i32 m0, s30, 0x2000
	s_nop 0
	global_load_lds_dwordx4 v132, s[20:21]
	v_lshl_add_u64 v[210:211], v[214:215], 0, s[28:29]
	s_mov_b32 m0, s18
	s_nop 0
	global_load_lds_dwordx4 v[210:211], off
	v_lshl_add_u64 v[210:211], v[216:217], 0, s[28:29]
	s_mov_b32 m0, s48
	s_nop 0
	global_load_lds_dwordx4 v[210:211], off
	s_waitcnt vmcnt(8)
	s_waitcnt lgkmcnt(0)
	s_barrier
	s_setprio 1
	s_waitcnt lgkmcnt(0)
	v_mfma_f32_16x16x32_bf16 v[64:67], v[142:145], v[178:181], v[64:67]
	v_mfma_f32_16x16x32_bf16 v[60:63], v[154:157], v[178:181], v[60:63]
	v_mfma_f32_16x16x32_bf16 v[56:59], v[142:145], v[186:189], v[56:59]
	v_mfma_f32_16x16x32_bf16 v[48:51], v[154:157], v[186:189], v[48:51]
	v_mfma_f32_16x16x32_bf16 v[40:43], v[142:145], v[194:197], v[40:43]
	v_mfma_f32_16x16x32_bf16 v[32:35], v[154:157], v[194:197], v[32:35]
	v_mfma_f32_16x16x32_bf16 v[24:27], v[142:145], v[202:205], v[24:27]
	v_mfma_f32_16x16x32_bf16 v[16:19], v[154:157], v[202:205], v[16:19]
	v_mfma_f32_16x16x32_bf16 v[64:67], v[150:153], v[182:185], v[64:67]
	v_mfma_f32_16x16x32_bf16 v[60:63], v[158:161], v[182:185], v[60:63]
	v_mfma_f32_16x16x32_bf16 v[56:59], v[150:153], v[190:193], v[56:59]
	v_mfma_f32_16x16x32_bf16 v[48:51], v[158:161], v[190:193], v[48:51]
	v_mfma_f32_16x16x32_bf16 v[40:43], v[150:153], v[198:201], v[40:43]
	v_mfma_f32_16x16x32_bf16 v[32:35], v[158:161], v[198:201], v[32:35]
	v_mfma_f32_16x16x32_bf16 v[24:27], v[150:153], v[206:209], v[24:27]
	v_mfma_f32_16x16x32_bf16 v[16:19], v[158:161], v[206:209], v[16:19]
	s_setprio 0
	s_setprio 1
	v_mfma_f32_16x16x32_bf16 v[52:55], v[162:165], v[178:181], v[52:55]
	v_mfma_f32_16x16x32_bf16 v[44:47], v[170:173], v[178:181], v[44:47]
	v_mfma_f32_16x16x32_bf16 v[36:39], v[162:165], v[186:189], v[36:39]
	v_mfma_f32_16x16x32_bf16 v[28:31], v[170:173], v[186:189], v[28:31]
	v_mfma_f32_16x16x32_bf16 v[20:23], v[162:165], v[194:197], v[20:23]
	v_mfma_f32_16x16x32_bf16 v[12:15], v[170:173], v[194:197], v[12:15]
	v_mfma_f32_16x16x32_bf16 v[8:11], v[162:165], v[202:205], v[8:11]
	v_mfma_f32_16x16x32_bf16 v[4:7], v[170:173], v[202:205], v[4:7]
	v_mfma_f32_16x16x32_bf16 v[52:55], v[166:169], v[182:185], v[52:55]
	v_mfma_f32_16x16x32_bf16 v[44:47], v[174:177], v[182:185], v[44:47]
	v_mfma_f32_16x16x32_bf16 v[36:39], v[166:169], v[190:193], v[36:39]
	v_mfma_f32_16x16x32_bf16 v[28:31], v[174:177], v[190:193], v[28:31]
	v_mfma_f32_16x16x32_bf16 v[20:23], v[166:169], v[198:201], v[20:23]
	v_mfma_f32_16x16x32_bf16 v[12:15], v[174:177], v[198:201], v[12:15]
	v_mfma_f32_16x16x32_bf16 v[8:11], v[166:169], v[206:209], v[8:11]
	v_mfma_f32_16x16x32_bf16 v[4:7], v[174:177], v[206:209], v[4:7]
	s_setprio 0
	s_barrier
	s_add_i32 s56, s56, 2
	s_add_u32 s54, s54, 0x100
	s_addc_u32 s55, s55, 0
	s_add_u32 s44, s44, 0x100
	s_addc_u32 s45, s45, 0
	s_cmp_gt_u32 s56, 29
	s_cbranch_scc0 .LBB0_310
	s_and_b64 vcc, exec, s[22:23]
	s_cbranch_vccz .LBB0_313
	s_barrier

; #define PG8_STAGE(bufoff, gbase, voff) do { _Pragma("unroll") for (int _i = 0; _i < 2; ++_i) \
;         __builtin_amdgcn_global_load_lds((const unsigned*)((const char*)(gbase) + (voff)[_i]), (PG8_LAS unsigned*)(lds + (bufoff) + ldsw + _i * 8192), 16, 0, 0); } while (0)
; #define PG8_WAIT_V(n) asm volatile("s_waitcnt vmcnt(" #n ")" ::: "memory")
; #define PG8_BAR __builtin_amdgcn_s_barrier()
; template <class Epi, class Sched, bool ALIGN_EPI = false, bool SP2 = false>
; __device__ __forceinline__ void gemm_phase(PG8_LAS unsigned char* lds, const Gemm g, const Sched& S, const Epi& E) {
;     ...
;     for (int i = 0; i < 2; ++i) { int R, C; stage_rc(tid * 16 + i * 8192, R, C); const int Rb = Epi::PERM ? ((R & ~31) + perm32(R & 31)) : R;
;         voffA[i] = (unsigned)(R * K + C) * 2u; voffB[i] = (unsigned)(Rb * K + C) * 2u; }
;     const size_t kstep = (size_t)(BK * 2);
;     const size_t hstep = (size_t)HALF * K * 2;
;     const size_t tstep = 2 * hstep;
;     const unsigned ldsw = (unsigned)wid * 1024u;
;     const int aoff = lds_byte(wr * 64 + fr, fq * 8), boff = lds_byte(wc * 32 + fr, fq * 8);
;     ...
;         PG8_WAIT_V(2); PG8_BAR;
;         PG8_STAGE(PG8_SB(1, 0), cB + kstep, voffB); PG8_STAGE(PG8_SA(1, 0), cA + kstep, voffA); PG8_STAGE(PG8_SB(1, 1), cB + hstep + kstep, voffB);
;         PG8_WAIT_V(6); PG8_BAR;
.LBB0_2159:
	v_lshrrev_b32_e32 v20, 1, v18
	s_add_u32 s16, s16, 0xe800000
	v_and_b32_e32 v20, 24, v20
	s_addc_u32 s17, s17, 0
	v_and_b32_e32 v19, 15, v18
	v_lshlrev_b32_e32 v21, 1, v20
	v_lshlrev_b32_e32 v18, 2, v18
	s_lshl_b32 s13, s13, 5
	s_sext_i32_i16 s4, s18
	v_lshl_or_b32 v1, s22, 6, v19
	v_lshl_or_b32 v19, v19, 6, v21
	s_lshl_b32 s18, s22, 13
	v_and_b32_e32 v18, 32, v18
	s_and_b32 s13, s13, 0x60
	v_bitop3_b32 v21, v19, s18, v18 bitop3:0xde
	s_lshl_b32 s18, s13, 7
	s_add_i32 m0, s43, 0x18000
	v_lshl_add_u64 v[10:11], v[10:11], 0, s[28:29]
	v_bitop3_b32 v146, v19, s18, v18 bitop3:0xde
	v_add_u32_e32 v252, 0x10000, v146
	s_waitcnt vmcnt(2)
	s_barrier
	global_load_lds_dwordx4 v[10:11], off
	v_lshl_add_u64 v[8:9], v[8:9], 0, s[28:29]
	s_add_i32 m0, s43, 0x1a000
	s_add_i32 s18, s43, 0x8000
	s_add_i32 s52, s43, 0xa000
	global_load_lds_dwordx4 v[8:9], off
	v_lshl_add_u64 v[4:5], v[4:5], 0, s[28:29]
	s_mov_b32 m0, s18
	s_add_u32 s22, s20, 0x80080
	global_load_lds_dwordx4 v[4:5], off
	v_lshl_add_u64 v[4:5], v[6:7], 0, s[28:29]
	s_mov_b32 m0, s52
	s_addc_u32 s23, s21, 0
	global_load_lds_dwordx4 v[4:5], off
	s_add_i32 m0, s43, 0x1c000
	s_nop 0
	global_load_lds_dwordx4 v2, s[22:23]
	v_lshl_add_u64 v[4:5], s[22:23], 0, v[132:133]
	s_add_i32 m0, s43, 0x1e000
	s_cmpk_lt_u32 s12, 0x100
	global_load_lds_dwordx4 v[4:5], off
	v_lshlrev_b32_e32 v4, 15, v12
	v_and_b32_e32 v4, 0xffff0000, v4
	v_lshl_add_u32 v4, v13, 12, v4
	v_and_b32_e32 v5, 1, v12
	v_lshl_or_b32 v4, v5, 6, v4
	v_lshl_add_u32 v138, v14, 1, v4
	v_lshlrev_b32_e32 v4, 15, v16
	v_and_b32_e32 v4, 0xffff0000, v4
	s_waitcnt vmcnt(6)
	v_lshl_add_u32 v4, v15, 12, v4
	v_and_b32_e32 v5, 1, v16
	v_lshl_or_b32 v4, v5, 6, v4
	s_cselect_b64 s[22:23], -1, 0
	s_ashr_i32 s53, s5, 31
	v_or_b32_e32 v147, s13, v20
	v_mov_b32_e32 v139, v3
	v_lshl_add_u32 v140, v17, 1, v4
	v_mov_b32_e32 v141, v3
	s_mov_b32 s54, 0
	v_add_u32_e32 v148, 0, v21
	s_barrier
	s_branch .LBB0_2162

; #define PG8_STAGE(bufoff, gbase, voff) do { _Pragma("unroll") for (int _i = 0; _i < 2; ++_i) \
;         __builtin_amdgcn_global_load_lds((const unsigned*)((const char*)(gbase) + (voff)[_i]), (PG8_LAS unsigned*)(lds + (bufoff) + ldsw + _i * 8192), 16, 0, 0); } while (0)
; #define PG8_LDA(dst, b, h) do { _Pragma("unroll") for (int m = 0; m < 4; ++m) _Pragma("unroll") for (int k = 0; k < 2; ++k) dst[m][k] = *(const PG8_LAS bf16x8*)(lds + PG8_SA(b, h) + aoff + m * 2048 + k * 1024); } while (0)
; #define PG8_LDB(dst, b, h) do { _Pragma("unroll") for (int n = 0; n < 2; ++n) _Pragma("unroll") for (int k = 0; k < 2; ++k) dst[n][k] = *(const PG8_LAS bf16x8*)(lds + PG8_SB(b, h) + boff + n * 2048 + k * 1024); } while (0)
; #define PG8_MMA(ai, bj, At, Bt) do { __builtin_amdgcn_s_setprio(1); _Pragma("unroll") for (int m = 0; m < 4; ++m) _Pragma("unroll") for (int n = 0; n < 2; ++n) _Pragma("unroll") for (int k = 0; k < 2; ++k) \
;         acc[ai][bj][m][n] = __builtin_amdgcn_mfma_f32_16x16x32_bf16(Bt[n][k], At[m][k], acc[ai][bj][m][n], 0, 0, 0); __builtin_amdgcn_s_setprio(0); } while (0)
; #define PG8_WAIT_V(n) asm volatile("s_waitcnt vmcnt(" #n ")" ::: "memory")
; #define PG8_WAIT_L(n) asm volatile("s_waitcnt lgkmcnt(" #n ")" ::: "memory")
; #define PG8_BAR __builtin_amdgcn_s_barrier()
; #define PG8_SCHED __builtin_amdgcn_sched_barrier(0)
; template <class Epi, class Sched, bool ALIGN_EPI = false, bool SP2 = false>
; __device__ __forceinline__ void gemm_phase(PG8_LAS unsigned char* lds, const Gemm g, const Sched& S, const Epi& E) {
;     ...
;             PG8_LDB(B0, 0, 0); PG8_LDB(B1, 0, 1); PG8_SCHED; PG8_LDA(At, 0, 0); PG8_STAGE(PG8_SA(1, 1), a1 + hstep, voffA);
;             PG8_WAIT_V(8); PG8_WAIT_L(0); PG8_BAR; PG8_MMA(0, 0, At, B0); PG8_MMA(0, 1, At, B1); PG8_BAR; PG8_SCHED;
;             PG8_LDA(At, 0, 1); PG8_STAGE(PG8_SB(0, 0), b2, voffB); PG8_STAGE(PG8_SB(0, 1), b2 + hstep, voffB); PG8_STAGE(PG8_SA(0, 0), a2, voffA);
;             PG8_WAIT_V(8); PG8_WAIT_L(0); PG8_BAR; PG8_MMA(1, 0, At, B0); PG8_MMA(1, 1, At, B1); PG8_BAR; PG8_SCHED;
.LBB0_2165:
	s_add_u32 s20, s44, 0xfff80080
	s_addc_u32 s21, s45, -1
	s_add_i32 s30, 0, 0x10000
	s_cmp_eq_u32 s56, 28
	s_cselect_b32 s47, s12, s21
	s_cselect_b32 s46, s13, s20
	s_cselect_b32 s21, s25, s55
	s_cselect_b32 s20, s27, s33
	s_add_i32 s57, 0, 0x14000
	ds_read_b128 v[142:145], v252
	ds_read_b128 v[150:153], v252 offset:1024
	ds_read_b128 v[154:157], v252 offset:2048
	ds_read_b128 v[158:161], v252 offset:3072
	ds_read_b128 v[162:165], v252 offset:16384
	ds_read_b128 v[166:169], v252 offset:17408
	ds_read_b128 v[170:173], v252 offset:18432
	ds_read_b128 v[174:177], v252 offset:19456
	s_add_i32 m0, s43, 0xc000
	ds_read_b128 v[178:181], v148
	ds_read_b128 v[182:185], v148 offset:1024
	ds_read_b128 v[186:189], v148 offset:2048
	ds_read_b128 v[190:193], v148 offset:3072
	ds_read_b128 v[194:197], v148 offset:4096
	ds_read_b128 v[198:201], v148 offset:5120
	ds_read_b128 v[202:205], v148 offset:6144
	ds_read_b128 v[206:209], v148 offset:7168
	global_load_lds_dwordx4 v140, s[44:45]
	s_add_i32 m0, s43, 0xe000
	s_nop 0
	global_load_lds_dwordx4 v138, s[44:45]
	s_waitcnt vmcnt(8)
	s_waitcnt lgkmcnt(0)
	s_barrier
	s_setprio 1
	s_waitcnt lgkmcnt(0)
	v_mfma_f32_16x16x32_bf16 v[128:131], v[142:145], v[178:181], v[128:131]
	v_mfma_f32_16x16x32_bf16 v[120:123], v[154:157], v[178:181], v[120:123]
	v_mfma_f32_16x16x32_bf16 v[112:115], v[142:145], v[186:189], v[112:115]
	v_mfma_f32_16x16x32_bf16 v[104:107], v[154:157], v[186:189], v[104:107]
	v_mfma_f32_16x16x32_bf16 v[96:99], v[142:145], v[194:197], v[96:99]
	v_mfma_f32_16x16x32_bf16 v[88:91], v[154:157], v[194:197], v[88:91]
	v_mfma_f32_16x16x32_bf16 v[80:83], v[142:145], v[202:205], v[80:83]
	v_mfma_f32_16x16x32_bf16 v[72:75], v[154:157], v[202:205], v[72:75]
	v_mfma_f32_16x16x32_bf16 v[128:131], v[150:153], v[182:185], v[128:131]
	v_mfma_f32_16x16x32_bf16 v[120:123], v[158:161], v[182:185], v[120:123]
	v_mfma_f32_16x16x32_bf16 v[112:115], v[150:153], v[190:193], v[112:115]
	v_mfma_f32_16x16x32_bf16 v[104:107], v[158:161], v[190:193], v[104:107]
	v_mfma_f32_16x16x32_bf16 v[96:99], v[150:153], v[198:201], v[96:99]
	v_mfma_f32_16x16x32_bf16 v[88:91], v[158:161], v[198:201], v[88:91]
	v_mfma_f32_16x16x32_bf16 v[80:83], v[150:153], v[206:209], v[80:83]
	v_mfma_f32_16x16x32_bf16 v[72:75], v[158:161], v[206:209], v[72:75]
	s_setprio 0
	s_setprio 1
	v_mfma_f32_16x16x32_bf16 v[124:127], v[162:165], v[178:181], v[124:127]
	v_mfma_f32_16x16x32_bf16 v[116:119], v[170:173], v[178:181], v[116:119]
	v_mfma_f32_16x16x32_bf16 v[108:111], v[162:165], v[186:189], v[108:111]
	v_mfma_f32_16x16x32_bf16 v[100:103], v[170:173], v[186:189], v[100:103]
	v_mfma_f32_16x16x32_bf16 v[92:95], v[162:165], v[194:197], v[92:95]
	v_mfma_f32_16x16x32_bf16 v[84:87], v[170:173], v[194:197], v[84:87]
	v_mfma_f32_16x16x32_bf16 v[76:79], v[162:165], v[202:205], v[76:79]
	v_mfma_f32_16x16x32_bf16 v[68:71], v[170:173], v[202:205], v[68:71]
	v_mfma_f32_16x16x32_bf16 v[124:127], v[166:169], v[182:185], v[124:127]
	v_mfma_f32_16x16x32_bf16 v[116:119], v[174:177], v[182:185], v[116:119]
	v_mfma_f32_16x16x32_bf16 v[108:111], v[166:169], v[190:193], v[108:111]
	v_mfma_f32_16x16x32_bf16 v[100:103], v[174:177], v[190:193], v[100:103]
	v_mfma_f32_16x16x32_bf16 v[92:95], v[166:169], v[198:201], v[92:95]
	v_mfma_f32_16x16x32_bf16 v[84:87], v[174:177], v[198:201], v[84:87]
	v_mfma_f32_16x16x32_bf16 v[76:79], v[166:169], v[206:209], v[76:79]
	v_mfma_f32_16x16x32_bf16 v[68:71], v[174:177], v[206:209], v[68:71]
	s_setprio 0
	s_barrier
	s_add_i32 s30, s30, s11
	v_lshl_add_u64 v[210:211], s[20:21], 0, v[2:3]
	s_mov_b32 m0, s30
	ds_read_b128 v[178:181], v148 offset:16384
	ds_read_b128 v[182:185], v148 offset:17408
	ds_read_b128 v[186:189], v148 offset:18432
	ds_read_b128 v[190:193], v148 offset:19456
	ds_read_b128 v[194:197], v148 offset:20480
	ds_read_b128 v[198:201], v148 offset:21504
	ds_read_b128 v[202:205], v148 offset:22528
	ds_read_b128 v[206:209], v148 offset:23552
	global_load_lds_dwordx4 v[210:211], off
	s_add_i32 m0, s30, 0x2000
	s_add_u32 s30, s20, 0x80000
	v_lshl_add_u64 v[212:213], s[20:21], 0, v[132:133]
	s_addc_u32 s31, s21, 0
	s_add_i32 s57, s57, s11
	global_load_lds_dwordx4 v[212:213], off
	s_mov_b32 m0, s57
	v_lshl_add_u64 v[216:217], s[46:47], 0, v[134:135]
	global_load_lds_dwordx4 v2, s[30:31]
	s_add_i32 m0, s57, 0x2000
	s_nop 0
	global_load_lds_dwordx4 v132, s[30:31]
	v_lshl_add_u64 v[214:215], s[46:47], 0, v[136:137]
	s_mov_b32 m0, s43
	s_nop 0
	global_load_lds_dwordx4 v[214:215], off
	s_mov_b32 m0, s49
	s_nop 0
	global_load_lds_dwordx4 v[216:217], off
	s_waitcnt vmcnt(8)
	s_waitcnt lgkmcnt(0)
	s_barrier
; #define PG8_STAGE(bufoff, gbase, voff) do { _Pragma("unroll") for (int _i = 0; _i < 2; ++_i) \
;         __builtin_amdgcn_global_load_lds((const unsigned*)((const char*)(gbase) + (voff)[_i]), (PG8_LAS unsigned*)(lds + (bufoff) + ldsw + _i * 8192), 16, 0, 0); } while (0)
; #define PG8_LDA(dst, b, h) do { _Pragma("unroll") for (int m = 0; m < 4; ++m) _Pragma("unroll") for (int k = 0; k < 2; ++k) dst[m][k] = *(const PG8_LAS bf16x8*)(lds + PG8_SA(b, h) + aoff + m * 2048 + k * 1024); } while (0)
; #define PG8_LDB(dst, b, h) do { _Pragma("unroll") for (int n = 0; n < 2; ++n) _Pragma("unroll") for (int k = 0; k < 2; ++k) dst[n][k] = *(const PG8_LAS bf16x8*)(lds + PG8_SB(b, h) + boff + n * 2048 + k * 1024); } while (0)
; #define PG8_MMA(ai, bj, At, Bt) do { __builtin_amdgcn_s_setprio(1); _Pragma("unroll") for (int m = 0; m < 4; ++m) _Pragma("unroll") for (int n = 0; n < 2; ++n) _Pragma("unroll") for (int k = 0; k < 2; ++k) \
;         acc[ai][bj][m][n] = __builtin_amdgcn_mfma_f32_16x16x32_bf16(Bt[n][k], At[m][k], acc[ai][bj][m][n], 0, 0, 0); __builtin_amdgcn_s_setprio(0); } while (0)
; #define PG8_WAIT_V(n) asm volatile("s_waitcnt vmcnt(" #n ")" ::: "memory")
; #define PG8_WAIT_L(n) asm volatile("s_waitcnt lgkmcnt(" #n ")" ::: "memory")
; #define PG8_BAR __builtin_amdgcn_s_barrier()
; #define PG8_SCHED __builtin_amdgcn_sched_barrier(0)
; template <class Epi, class Sched, bool ALIGN_EPI = false, bool SP2 = false>
; __device__ __forceinline__ void gemm_phase(PG8_LAS unsigned char* lds, const Gemm g, const Sched& S, const Epi& E) {
;     ...
;             PG8_WAIT_V(8); PG8_WAIT_L(0); PG8_BAR; PG8_MMA(1, 0, At, B0); PG8_MMA(1, 1, At, B1); PG8_BAR; PG8_SCHED;
;             PG8_LDB(B0, 1, 0); PG8_LDB(B1, 1, 1); PG8_SCHED; PG8_LDA(At, 1, 0); PG8_STAGE(PG8_SA(0, 1), a2 + hstep, voffA);
;             PG8_WAIT_V(8); PG8_WAIT_L(0); PG8_BAR; PG8_MMA(0, 0, At, B0); PG8_MMA(0, 1, At, B1); PG8_BAR; PG8_SCHED;
	s_setprio 1
	s_waitcnt lgkmcnt(0)
	v_mfma_f32_16x16x32_bf16 v[64:67], v[142:145], v[178:181], v[64:67]
	v_mfma_f32_16x16x32_bf16 v[56:59], v[154:157], v[178:181], v[56:59]
	v_mfma_f32_16x16x32_bf16 v[48:51], v[142:145], v[186:189], v[48:51]
	v_mfma_f32_16x16x32_bf16 v[40:43], v[154:157], v[186:189], v[40:43]
	v_mfma_f32_16x16x32_bf16 v[32:35], v[142:145], v[194:197], v[32:35]
	v_mfma_f32_16x16x32_bf16 v[24:27], v[154:157], v[194:197], v[24:27]
	v_mfma_f32_16x16x32_bf16 v[16:19], v[142:145], v[202:205], v[16:19]
	v_mfma_f32_16x16x32_bf16 v[8:11], v[154:157], v[202:205], v[8:11]
	v_mfma_f32_16x16x32_bf16 v[64:67], v[150:153], v[182:185], v[64:67]
	v_mfma_f32_16x16x32_bf16 v[56:59], v[158:161], v[182:185], v[56:59]
	v_mfma_f32_16x16x32_bf16 v[48:51], v[150:153], v[190:193], v[48:51]
	v_mfma_f32_16x16x32_bf16 v[40:43], v[158:161], v[190:193], v[40:43]
	v_mfma_f32_16x16x32_bf16 v[32:35], v[150:153], v[198:201], v[32:35]
	v_mfma_f32_16x16x32_bf16 v[24:27], v[158:161], v[198:201], v[24:27]
	v_mfma_f32_16x16x32_bf16 v[16:19], v[150:153], v[206:209], v[16:19]
	v_mfma_f32_16x16x32_bf16 v[8:11], v[158:161], v[206:209], v[8:11]
	s_setprio 0
	s_setprio 1
	v_mfma_f32_16x16x32_bf16 v[60:63], v[162:165], v[178:181], v[60:63]
	v_mfma_f32_16x16x32_bf16 v[52:55], v[170:173], v[178:181], v[52:55]
	v_mfma_f32_16x16x32_bf16 v[44:47], v[162:165], v[186:189], v[44:47]
	v_mfma_f32_16x16x32_bf16 v[36:39], v[170:173], v[186:189], v[36:39]
	v_mfma_f32_16x16x32_bf16 v[28:31], v[162:165], v[194:197], v[28:31]
	v_mfma_f32_16x16x32_bf16 v[20:23], v[170:173], v[194:197], v[20:23]
	v_mfma_f32_16x16x32_bf16 v[12:15], v[162:165], v[202:205], v[12:15]
	v_mfma_f32_16x16x32_bf16 v[4:7], v[170:173], v[202:205], v[4:7]
	v_mfma_f32_16x16x32_bf16 v[60:63], v[166:169], v[182:185], v[60:63]
	v_mfma_f32_16x16x32_bf16 v[52:55], v[174:177], v[182:185], v[52:55]
	v_mfma_f32_16x16x32_bf16 v[44:47], v[166:169], v[190:193], v[44:47]
	v_mfma_f32_16x16x32_bf16 v[36:39], v[174:177], v[190:193], v[36:39]
	v_mfma_f32_16x16x32_bf16 v[28:31], v[166:169], v[198:201], v[28:31]
	v_mfma_f32_16x16x32_bf16 v[20:23], v[174:177], v[198:201], v[20:23]
	v_mfma_f32_16x16x32_bf16 v[12:15], v[166:169], v[206:209], v[12:15]
	v_mfma_f32_16x16x32_bf16 v[4:7], v[174:177], v[206:209], v[4:7]
	s_setprio 0
	s_barrier
	s_add_i32 s57, 0, 0x18000
	s_add_i32 s58, 0, 0x1c000
	ds_read_b128 v[142:145], v252 offset:32768
	ds_read_b128 v[150:153], v252 offset:33792
	ds_read_b128 v[154:157], v252 offset:34816
	ds_read_b128 v[158:161], v252 offset:35840
	ds_read_b128 v[162:165], v252 offset:49152
	ds_read_b128 v[166:169], v252 offset:50176
	ds_read_b128 v[170:173], v252 offset:51200
	ds_read_b128 v[174:177], v252 offset:52224
	s_add_u32 s30, s46, 0x80000
	s_addc_u32 s31, s47, 0
	s_mov_b32 m0, s50
	ds_read_b128 v[178:181], v148 offset:32768
	ds_read_b128 v[182:185], v148 offset:33792
	ds_read_b128 v[186:189], v148 offset:34816
	ds_read_b128 v[190:193], v148 offset:35840
	ds_read_b128 v[194:197], v148 offset:36864
	ds_read_b128 v[198:201], v148 offset:37888
	ds_read_b128 v[202:205], v148 offset:38912
	ds_read_b128 v[206:209], v148 offset:39936
	global_load_lds_dwordx4 v136, s[30:31]
	s_mov_b32 m0, s51
	s_nop 0
	global_load_lds_dwordx4 v134, s[30:31]
	s_waitcnt vmcnt(8)
	s_waitcnt lgkmcnt(0)
	s_barrier
	s_setprio 1
	s_waitcnt lgkmcnt(0)
	v_mfma_f32_16x16x32_bf16 v[128:131], v[142:145], v[178:181], v[128:131]
	v_mfma_f32_16x16x32_bf16 v[120:123], v[154:157], v[178:181], v[120:123]
	v_mfma_f32_16x16x32_bf16 v[112:115], v[142:145], v[186:189], v[112:115]
	v_mfma_f32_16x16x32_bf16 v[104:107], v[154:157], v[186:189], v[104:107]
	v_mfma_f32_16x16x32_bf16 v[96:99], v[142:145], v[194:197], v[96:99]
	v_mfma_f32_16x16x32_bf16 v[88:91], v[154:157], v[194:197], v[88:91]
	v_mfma_f32_16x16x32_bf16 v[80:83], v[142:145], v[202:205], v[80:83]
	v_mfma_f32_16x16x32_bf16 v[72:75], v[154:157], v[202:205], v[72:75]
	v_mfma_f32_16x16x32_bf16 v[128:131], v[150:153], v[182:185], v[128:131]
	v_mfma_f32_16x16x32_bf16 v[120:123], v[158:161], v[182:185], v[120:123]
	v_mfma_f32_16x16x32_bf16 v[112:115], v[150:153], v[190:193], v[112:115]
	v_mfma_f32_16x16x32_bf16 v[104:107], v[158:161], v[190:193], v[104:107]
	v_mfma_f32_16x16x32_bf16 v[96:99], v[150:153], v[198:201], v[96:99]
	v_mfma_f32_16x16x32_bf16 v[88:91], v[158:161], v[198:201], v[88:91]
	v_mfma_f32_16x16x32_bf16 v[80:83], v[150:153], v[206:209], v[80:83]
	v_mfma_f32_16x16x32_bf16 v[72:75], v[158:161], v[206:209], v[72:75]
	s_setprio 0
	s_setprio 1
	v_mfma_f32_16x16x32_bf16 v[124:127], v[162:165], v[178:181], v[124:127]
	v_mfma_f32_16x16x32_bf16 v[116:119], v[170:173], v[178:181], v[116:119]
	v_mfma_f32_16x16x32_bf16 v[108:111], v[162:165], v[186:189], v[108:111]
	v_mfma_f32_16x16x32_bf16 v[100:103], v[170:173], v[186:189], v[100:103]
	v_mfma_f32_16x16x32_bf16 v[92:95], v[162:165], v[194:197], v[92:95]
	v_mfma_f32_16x16x32_bf16 v[84:87], v[170:173], v[194:197], v[84:87]
	v_mfma_f32_16x16x32_bf16 v[76:79], v[162:165], v[202:205], v[76:79]
	v_mfma_f32_16x16x32_bf16 v[68:71], v[170:173], v[202:205], v[68:71]
	v_mfma_f32_16x16x32_bf16 v[124:127], v[166:169], v[182:185], v[124:127]
	v_mfma_f32_16x16x32_bf16 v[116:119], v[174:177], v[182:185], v[116:119]
	v_mfma_f32_16x16x32_bf16 v[108:111], v[166:169], v[190:193], v[108:111]
	v_mfma_f32_16x16x32_bf16 v[100:103], v[174:177], v[190:193], v[100:103]
	v_mfma_f32_16x16x32_bf16 v[92:95], v[166:169], v[198:201], v[92:95]
	v_mfma_f32_16x16x32_bf16 v[84:87], v[174:177], v[198:201], v[84:87]
	v_mfma_f32_16x16x32_bf16 v[76:79], v[166:169], v[206:209], v[76:79]
	v_mfma_f32_16x16x32_bf16 v[68:71], v[174:177], v[206:209], v[68:71]
	s_setprio 0
	s_barrier
; #define PG8_STAGE(bufoff, gbase, voff) do { _Pragma("unroll") for (int _i = 0; _i < 2; ++_i) \
;         __builtin_amdgcn_global_load_lds((const unsigned*)((const char*)(gbase) + (voff)[_i]), (PG8_LAS unsigned*)(lds + (bufoff) + ldsw + _i * 8192), 16, 0, 0); } while (0)
; #define PG8_LDA(dst, b, h) do { _Pragma("unroll") for (int m = 0; m < 4; ++m) _Pragma("unroll") for (int k = 0; k < 2; ++k) dst[m][k] = *(const PG8_LAS bf16x8*)(lds + PG8_SA(b, h) + aoff + m * 2048 + k * 1024); } while (0)
; #define PG8_MMA(ai, bj, At, Bt) do { __builtin_amdgcn_s_setprio(1); _Pragma("unroll") for (int m = 0; m < 4; ++m) _Pragma("unroll") for (int n = 0; n < 2; ++n) _Pragma("unroll") for (int k = 0; k < 2; ++k) \
;         acc[ai][bj][m][n] = __builtin_amdgcn_mfma_f32_16x16x32_bf16(Bt[n][k], At[m][k], acc[ai][bj][m][n], 0, 0, 0); __builtin_amdgcn_s_setprio(0); } while (0)
; #define PG8_WAIT_V(n) asm volatile("s_waitcnt vmcnt(" #n ")" ::: "memory")
; #define PG8_WAIT_L(n) asm volatile("s_waitcnt lgkmcnt(" #n ")" ::: "memory")
; #define PG8_BAR __builtin_amdgcn_s_barrier()
; #define PG8_SCHED __builtin_amdgcn_sched_barrier(0)
; template <class Epi, class Sched, bool ALIGN_EPI = false, bool SP2 = false>
; __device__ __forceinline__ void gemm_phase(PG8_LAS unsigned char* lds, const Gemm g, const Sched& S, const Epi& E) {
;     ...
;             PG8_LDA(At, 1, 1); PG8_STAGE(PG8_SB(1, 0), b3, voffB); PG8_STAGE(PG8_SB(1, 1), b3 + hstep, voffB); PG8_STAGE(PG8_SA(1, 0), a3, voffA);
;             PG8_WAIT_V(8); PG8_WAIT_L(0); PG8_BAR; PG8_MMA(1, 0, At, B0); PG8_MMA(1, 1, At, B1); PG8_BAR; PG8_SCHED;
;     ...
;         if constexpr (ALIGN_EPI) { if (wr == 0) PG8_BAR; }
	s_add_i32 s30, s57, s11
	v_lshl_add_u64 v[210:211], v[210:211], 0, s[28:29]
	s_mov_b32 m0, s30
	ds_read_b128 v[178:181], v148 offset:49152
	ds_read_b128 v[182:185], v148 offset:50176
	ds_read_b128 v[186:189], v148 offset:51200
	ds_read_b128 v[190:193], v148 offset:52224
	ds_read_b128 v[194:197], v148 offset:53248
	ds_read_b128 v[198:201], v148 offset:54272
	ds_read_b128 v[202:205], v148 offset:55296
	ds_read_b128 v[206:209], v148 offset:56320
	global_load_lds_dwordx4 v[210:211], off
	s_add_i32 m0, s30, 0x2000
	s_add_u32 s20, s20, 0x80080
	v_lshl_add_u64 v[210:211], v[212:213], 0, s[28:29]
	s_addc_u32 s21, s21, 0
	s_add_i32 s30, s58, s11
	global_load_lds_dwordx4 v[210:211], off
	s_mov_b32 m0, s30
	s_nop 0
	global_load_lds_dwordx4 v2, s[20:21]
	s_add_i32 m0, s30, 0x2000
	s_nop 0
	global_load_lds_dwordx4 v132, s[20:21]
	v_lshl_add_u64 v[210:211], v[214:215], 0, s[28:29]
	s_mov_b32 m0, s18
	s_nop 0
	global_load_lds_dwordx4 v[210:211], off
	v_lshl_add_u64 v[210:211], v[216:217], 0, s[28:29]
	s_mov_b32 m0, s52
	s_nop 0
	global_load_lds_dwordx4 v[210:211], off
	s_waitcnt vmcnt(8)
	s_waitcnt lgkmcnt(0)
	s_barrier
	s_setprio 1
	s_waitcnt lgkmcnt(0)
	v_mfma_f32_16x16x32_bf16 v[64:67], v[142:145], v[178:181], v[64:67]
	v_mfma_f32_16x16x32_bf16 v[56:59], v[154:157], v[178:181], v[56:59]
	v_mfma_f32_16x16x32_bf16 v[48:51], v[142:145], v[186:189], v[48:51]
	v_mfma_f32_16x16x32_bf16 v[40:43], v[154:157], v[186:189], v[40:43]
	v_mfma_f32_16x16x32_bf16 v[32:35], v[142:145], v[194:197], v[32:35]
	v_mfma_f32_16x16x32_bf16 v[24:27], v[154:157], v[194:197], v[24:27]
	v_mfma_f32_16x16x32_bf16 v[16:19], v[142:145], v[202:205], v[16:19]
	v_mfma_f32_16x16x32_bf16 v[8:11], v[154:157], v[202:205], v[8:11]
	v_mfma_f32_16x16x32_bf16 v[64:67], v[150:153], v[182:185], v[64:67]
	v_mfma_f32_16x16x32_bf16 v[56:59], v[158:161], v[182:185], v[56:59]
	v_mfma_f32_16x16x32_bf16 v[48:51], v[150:153], v[190:193], v[48:51]
	v_mfma_f32_16x16x32_bf16 v[40:43], v[158:161], v[190:193], v[40:43]
	v_mfma_f32_16x16x32_bf16 v[32:35], v[150:153], v[198:201], v[32:35]
	v_mfma_f32_16x16x32_bf16 v[24:27], v[158:161], v[198:201], v[24:27]
	v_mfma_f32_16x16x32_bf16 v[16:19], v[150:153], v[206:209], v[16:19]
	v_mfma_f32_16x16x32_bf16 v[8:11], v[158:161], v[206:209], v[8:11]
	s_setprio 0
	s_setprio 1
	v_mfma_f32_16x16x32_bf16 v[60:63], v[162:165], v[178:181], v[60:63]
	v_mfma_f32_16x16x32_bf16 v[52:55], v[170:173], v[178:181], v[52:55]
	v_mfma_f32_16x16x32_bf16 v[44:47], v[162:165], v[186:189], v[44:47]
	v_mfma_f32_16x16x32_bf16 v[36:39], v[170:173], v[186:189], v[36:39]
	v_mfma_f32_16x16x32_bf16 v[28:31], v[162:165], v[194:197], v[28:31]
	v_mfma_f32_16x16x32_bf16 v[20:23], v[170:173], v[194:197], v[20:23]
	v_mfma_f32_16x16x32_bf16 v[12:15], v[162:165], v[202:205], v[12:15]
	v_mfma_f32_16x16x32_bf16 v[4:7], v[170:173], v[202:205], v[4:7]
	v_mfma_f32_16x16x32_bf16 v[60:63], v[166:169], v[182:185], v[60:63]
	v_mfma_f32_16x16x32_bf16 v[52:55], v[174:177], v[182:185], v[52:55]
	v_mfma_f32_16x16x32_bf16 v[44:47], v[166:169], v[190:193], v[44:47]
	v_mfma_f32_16x16x32_bf16 v[36:39], v[174:177], v[190:193], v[36:39]
	v_mfma_f32_16x16x32_bf16 v[28:31], v[166:169], v[198:201], v[28:31]
	v_mfma_f32_16x16x32_bf16 v[20:23], v[174:177], v[198:201], v[20:23]
	v_mfma_f32_16x16x32_bf16 v[12:15], v[166:169], v[206:209], v[12:15]
	v_mfma_f32_16x16x32_bf16 v[4:7], v[174:177], v[206:209], v[4:7]
	s_setprio 0
	s_barrier
	s_add_i32 s56, s56, 2
	s_add_u32 s33, s33, 0x100
	s_addc_u32 s55, s55, 0
	s_add_u32 s44, s44, 0x100
	s_addc_u32 s45, s45, 0
	s_cmp_gt_u32 s56, 29
	s_cbranch_scc0 .LBB0_2165
	s_and_b64 vcc, exec, s[22:23]
	s_cbranch_vccz .LBB0_2168
	s_barrier
